# batched mode-6 epilogue and batched mid-loop gate rescale (no mode-7 epilogue change)
# speedup vs baseline: 1.0070x; 1.0070x over previous
; DEVI f32x4 ld_bf4(const bf16_t* p) { u32x2 u = *(const u32x2*)p; return (f32x4){bf_lo(u.x), bf_hi(u.x), bf_lo(u.y), bf_hi(u.y)}; }
; DEVI void gemm_tile(const GJob& jb, int brow, int bcol, unsigned char* shm_) {
;     ...
;     if (jb.mode == 7 && (t == 16 || t == 32)) {
;       const int seg = (t >> 4) - 1;
;       const bf16_t* gp = (const bf16_t*)jb.aux + (size_t)(brow + wr * 64 + fr) * NGATE + seg * 2048 + bcol + wc * 32 + fq * 8;
; #pragma unroll
;       for (int ai = 0; ai < 2; ++ai)
; #pragma unroll
;         for (int m = 0; m < 4; ++m)
; #pragma unroll
;           for (int bj = 0; bj < 2; ++bj)
; #pragma unroll
;             for (int n = 0; n < 2; ++n) {
;               const bf16_t* g = gp + (size_t)(ai * HALF + m * 16) * NGATE + bj * HALF + n * 4;
;               const f32x4 g0 = ld_bf4(g), g1 = ld_bf4(g + 2048);
; #pragma unroll
;               for (int e = 0; e < 4; ++e) acc[ai][bj][m][n][e] *= g0[e] * __builtin_amdgcn_rcpf(fmaxf(g1[e], 1e-30f));
;             }
.LBB0_420:
	s_andn2_b64 vcc, exec, s[8:9]
	s_cbranch_vccnz .LBB0_414
	v_add_co_u32_e32 v130, vcc, 0xffdeeef8, v140
	s_mov_b32 s0, 0xffdeeff8
	s_nop 0
	v_addc_co_u32_e32 v131, vcc, -1, v141, vcc
	v_add_co_u32_e32 v134, vcc, 0xffdefef8, v140
	global_load_dwordx4 v[130:133], v[130:131], off
	s_nop 0
	v_addc_co_u32_e32 v135, vcc, -1, v141, vcc
	global_load_dwordx4 v[134:137], v[134:135], off
	v_add_co_u32_e32 v170, vcc, s0, v140
	s_mov_b32 s0, 0xffdefff8
	s_nop 0
	v_addc_co_u32_e32 v171, vcc, -1, v141, vcc
	v_add_co_u32_e32 v174, vcc, s0, v140
	global_load_dwordx4 v[170:173], v[170:171], off
	s_nop 0
	v_addc_co_u32_e32 v175, vcc, -1, v141, vcc
	global_load_dwordx4 v[174:177], v[174:175], off
	s_mov_b32 s0, 0xffe1eef8
	v_add_co_u32_e32 v194, vcc, s0, v140
	s_mov_b32 s0, 0xffe1eff8
	s_nop 0
	v_addc_co_u32_e32 v195, vcc, -1, v141, vcc
	v_add_co_u32_e32 v162, vcc, s0, v140
	global_load_dwordx4 v[194:197], v[194:195], off
	s_nop 0
	v_addc_co_u32_e32 v163, vcc, -1, v141, vcc
	global_load_dwordx4 v[198:201], v[162:163], off offset:3840
	s_mov_b32 s0, 0xffe1fff8
	v_add_co_u32_e32 v206, vcc, s0, v140
	v_addc_co_u32_e32 v207, vcc, -1, v141, vcc
	global_load_dwordx4 v[202:205], v[162:163], off
	s_mov_b32 s0, 0xffe4eef8
	global_load_dwordx4 v[206:209], v[206:207], off
	v_add_co_u32_e32 v210, vcc, s0, v140
	s_mov_b32 s0, 0xffe4eff8
	s_nop 0
	v_addc_co_u32_e32 v211, vcc, -1, v141, vcc
	v_add_co_u32_e32 v162, vcc, s0, v140
	global_load_dwordx4 v[210:213], v[210:211], off
	s_nop 0
	v_addc_co_u32_e32 v163, vcc, -1, v141, vcc
	global_load_dwordx4 v[214:217], v[162:163], off offset:3840
	s_mov_b32 s0, 0xffe4fff8
	v_add_co_u32_e32 v222, vcc, s0, v140
	v_addc_co_u32_e32 v223, vcc, -1, v141, vcc
	global_load_dwordx4 v[218:221], v[162:163], off
	s_mov_b32 s0, 0xffe7eef8
	global_load_dwordx4 v[222:225], v[222:223], off
	v_add_co_u32_e32 v226, vcc, s0, v140
	s_mov_b32 s0, 0xffe7eff8
	s_nop 0
	v_addc_co_u32_e32 v227, vcc, -1, v141, vcc
	v_add_co_u32_e32 v162, vcc, s0, v140
	global_load_dwordx4 v[226:229], v[226:227], off
	s_nop 0
	v_addc_co_u32_e32 v163, vcc, -1, v141, vcc
	global_load_dwordx4 v[230:233], v[162:163], off offset:3840
	s_mov_b32 s0, 0xffe7fff8
	v_add_co_u32_e32 v238, vcc, s0, v140
	v_addc_co_u32_e32 v239, vcc, -1, v141, vcc
	global_load_dwordx4 v[234:237], v[162:163], off
	s_mov_b32 s0, 0xfff6eef8
	global_load_dwordx4 v[238:241], v[238:239], off
	s_waitcnt vmcnt(14)
	v_lshlrev_b32_e32 v162, 16, v134
	v_and_b32_e32 v163, 0xffff0000, v134
	v_lshlrev_b32_e32 v164, 16, v135
	v_and_b32_e32 v165, 0xffff0000, v135
	v_max_f32_e32 v134, v162, v162
	v_max_f32_e32 v135, v163, v163
	v_max_f32_e32 v134, 0xda24260, v134
	v_max_f32_e32 v135, 0xda24260, v135
	v_rcp_f32_e32 v134, v134
	v_rcp_f32_e32 v135, v135
	v_lshlrev_b32_e32 v162, 16, v130
	v_and_b32_e32 v163, 0xffff0000, v130
	v_max_f32_e32 v130, v164, v164
	v_pk_mul_f32 v[134:135], v[134:135], v[162:163]
	v_max_f32_e32 v130, 0xda24260, v130
	v_pk_mul_f32 v[122:123], v[122:123], v[134:135]
	v_rcp_f32_e32 v134, v130
	v_max_f32_e32 v130, v165, v165
	v_max_f32_e32 v130, 0xda24260, v130
	v_rcp_f32_e32 v135, v130
	v_lshlrev_b32_e32 v130, 16, v131
	v_and_b32_e32 v131, 0xffff0000, v131
	v_pk_mul_f32 v[130:131], v[134:135], v[130:131]
	s_nop 0
	v_pk_mul_f32 v[124:125], v[124:125], v[130:131]
	v_lshlrev_b32_e32 v130, 16, v136
	v_and_b32_e32 v131, 0xffff0000, v136
	v_max_f32_e32 v130, v130, v130
	v_max_f32_e32 v131, v131, v131
	v_max_f32_e32 v130, 0xda24260, v130
	v_max_f32_e32 v131, 0xda24260, v131
	v_rcp_f32_e32 v130, v130
	v_rcp_f32_e32 v131, v131
	v_lshlrev_b32_e32 v134, 16, v132
	v_and_b32_e32 v135, 0xffff0000, v132
	v_lshlrev_b32_e32 v136, 16, v137
	v_and_b32_e32 v137, 0xffff0000, v137
	v_pk_mul_f32 v[130:131], v[130:131], v[134:135]
	v_lshlrev_b32_e32 v132, 16, v133
	v_pk_mul_f32 v[126:127], v[126:127], v[130:131]
	v_max_f32_e32 v130, v136, v136
	v_max_f32_e32 v131, v137, v137
	v_max_f32_e32 v130, 0xda24260, v130
	v_max_f32_e32 v131, 0xda24260, v131
	v_rcp_f32_e32 v130, v130
	v_rcp_f32_e32 v131, v131
	v_and_b32_e32 v133, 0xffff0000, v133
	v_pk_mul_f32 v[130:131], v[130:131], v[132:133]
	s_nop 0
	v_pk_mul_f32 v[128:129], v[128:129], v[130:131]
	s_waitcnt vmcnt(12)
	v_lshlrev_b32_e32 v162, 16, v174
	v_and_b32_e32 v163, 0xffff0000, v174
	v_lshlrev_b32_e32 v164, 16, v175
	v_and_b32_e32 v165, 0xffff0000, v175
	v_max_f32_e32 v174, v162, v162
	v_max_f32_e32 v175, v163, v163
	v_max_f32_e32 v174, 0xda24260, v174
	v_max_f32_e32 v175, 0xda24260, v175
	v_rcp_f32_e32 v174, v174
	v_rcp_f32_e32 v175, v175
	v_lshlrev_b32_e32 v162, 16, v170
	v_and_b32_e32 v163, 0xffff0000, v170
	v_max_f32_e32 v170, v164, v164
	v_pk_mul_f32 v[174:175], v[174:175], v[162:163]
	v_max_f32_e32 v170, 0xda24260, v170
	v_pk_mul_f32 v[94:95], v[94:95], v[174:175]
	v_rcp_f32_e32 v174, v170
	v_max_f32_e32 v170, v165, v165
	v_max_f32_e32 v170, 0xda24260, v170
	v_rcp_f32_e32 v175, v170
	v_lshlrev_b32_e32 v170, 16, v171
	v_and_b32_e32 v171, 0xffff0000, v171
	v_pk_mul_f32 v[170:171], v[174:175], v[170:171]
	s_nop 0
	v_pk_mul_f32 v[96:97], v[96:97], v[170:171]
	v_lshlrev_b32_e32 v170, 16, v176
	v_and_b32_e32 v171, 0xffff0000, v176
	v_max_f32_e32 v170, v170, v170
	v_max_f32_e32 v171, v171, v171
	v_max_f32_e32 v170, 0xda24260, v170
	v_max_f32_e32 v171, 0xda24260, v171
	v_rcp_f32_e32 v170, v170
	v_rcp_f32_e32 v171, v171
	v_lshlrev_b32_e32 v174, 16, v172
	v_and_b32_e32 v175, 0xffff0000, v172
	v_lshlrev_b32_e32 v176, 16, v177
	v_and_b32_e32 v177, 0xffff0000, v177
	v_pk_mul_f32 v[170:171], v[170:171], v[174:175]
	v_lshlrev_b32_e32 v172, 16, v173
	v_pk_mul_f32 v[90:91], v[90:91], v[170:171]
	v_max_f32_e32 v170, v176, v176
	v_max_f32_e32 v171, v177, v177
	v_max_f32_e32 v170, 0xda24260, v170
	v_max_f32_e32 v171, 0xda24260, v171
	v_rcp_f32_e32 v170, v170
	v_rcp_f32_e32 v171, v171
	v_and_b32_e32 v173, 0xffff0000, v173
	v_pk_mul_f32 v[170:171], v[170:171], v[172:173]
	s_nop 0
	v_pk_mul_f32 v[92:93], v[92:93], v[170:171]
	s_waitcnt vmcnt(10)
; DEVI f32x4 ld_bf4(const bf16_t* p) { u32x2 u = *(const u32x2*)p; return (f32x4){bf_lo(u.x), bf_hi(u.x), bf_lo(u.y), bf_hi(u.y)}; }
; DEVI void gemm_tile(const GJob& jb, int brow, int bcol, unsigned char* shm_) {
;     ...
;     if (jb.mode == 7 && (t == 16 || t == 32)) {
;       const int seg = (t >> 4) - 1;
;       const bf16_t* gp = (const bf16_t*)jb.aux + (size_t)(brow + wr * 64 + fr) * NGATE + seg * 2048 + bcol + wc * 32 + fq * 8;
; #pragma unroll
;       for (int ai = 0; ai < 2; ++ai)
; #pragma unroll
;         for (int m = 0; m < 4; ++m)
; #pragma unroll
;           for (int bj = 0; bj < 2; ++bj)
; #pragma unroll
;             for (int n = 0; n < 2; ++n) {
;               const bf16_t* g = gp + (size_t)(ai * HALF + m * 16) * NGATE + bj * HALF + n * 4;
;               const f32x4 g0 = ld_bf4(g), g1 = ld_bf4(g + 2048);
; #pragma unroll
;               for (int e = 0; e < 4; ++e) acc[ai][bj][m][n][e] *= g0[e] * __builtin_amdgcn_rcpf(fmaxf(g1[e], 1e-30f));
;             }
	v_lshlrev_b32_e32 v164, 16, v198
	v_and_b32_e32 v165, 0xffff0000, v198
	v_lshlrev_b32_e32 v166, 16, v199
	v_and_b32_e32 v167, 0xffff0000, v199
	v_max_f32_e32 v198, v164, v164
	v_max_f32_e32 v199, v165, v165
	v_max_f32_e32 v198, 0xda24260, v198
	v_max_f32_e32 v199, 0xda24260, v199
	v_rcp_f32_e32 v198, v198
	v_rcp_f32_e32 v199, v199
	v_lshlrev_b32_e32 v164, 16, v194
	v_and_b32_e32 v165, 0xffff0000, v194
	v_max_f32_e32 v194, v166, v166
	v_pk_mul_f32 v[198:199], v[198:199], v[164:165]
	v_max_f32_e32 v194, 0xda24260, v194
	v_pk_mul_f32 v[118:119], v[118:119], v[198:199]
	v_rcp_f32_e32 v198, v194
	v_max_f32_e32 v194, v167, v167
	v_max_f32_e32 v194, 0xda24260, v194
	v_rcp_f32_e32 v199, v194
	v_lshlrev_b32_e32 v194, 16, v195
	v_and_b32_e32 v195, 0xffff0000, v195
	v_pk_mul_f32 v[194:195], v[198:199], v[194:195]
	s_nop 0
	v_pk_mul_f32 v[120:121], v[120:121], v[194:195]
	v_lshlrev_b32_e32 v194, 16, v200
	v_and_b32_e32 v195, 0xffff0000, v200
	v_max_f32_e32 v194, v194, v194
	v_max_f32_e32 v195, v195, v195
	v_max_f32_e32 v194, 0xda24260, v194
	v_max_f32_e32 v195, 0xda24260, v195
	v_rcp_f32_e32 v194, v194
	v_rcp_f32_e32 v195, v195
	v_lshlrev_b32_e32 v198, 16, v196
	v_and_b32_e32 v199, 0xffff0000, v196
	v_lshlrev_b32_e32 v200, 16, v201
	v_and_b32_e32 v201, 0xffff0000, v201
	v_pk_mul_f32 v[194:195], v[194:195], v[198:199]
	v_lshlrev_b32_e32 v196, 16, v197
	v_pk_mul_f32 v[114:115], v[114:115], v[194:195]
	v_max_f32_e32 v194, v200, v200
	v_max_f32_e32 v195, v201, v201
	v_max_f32_e32 v194, 0xda24260, v194
	v_max_f32_e32 v195, 0xda24260, v195
	v_rcp_f32_e32 v194, v194
	v_rcp_f32_e32 v195, v195
	v_and_b32_e32 v197, 0xffff0000, v197
	v_pk_mul_f32 v[194:195], v[194:195], v[196:197]
	s_nop 0
	v_pk_mul_f32 v[116:117], v[116:117], v[194:195]
	s_waitcnt vmcnt(8)
	v_lshlrev_b32_e32 v162, 16, v206
	v_and_b32_e32 v163, 0xffff0000, v206
	v_lshlrev_b32_e32 v164, 16, v207
	v_and_b32_e32 v165, 0xffff0000, v207
	v_max_f32_e32 v206, v162, v162
	v_max_f32_e32 v207, v163, v163
	v_max_f32_e32 v206, 0xda24260, v206
	v_max_f32_e32 v207, 0xda24260, v207
	v_rcp_f32_e32 v206, v206
	v_rcp_f32_e32 v207, v207
	v_lshlrev_b32_e32 v162, 16, v202
	v_and_b32_e32 v163, 0xffff0000, v202
	v_max_f32_e32 v202, v164, v164
	v_pk_mul_f32 v[206:207], v[206:207], v[162:163]
	v_max_f32_e32 v202, 0xda24260, v202
	v_pk_mul_f32 v[86:87], v[86:87], v[206:207]
	v_rcp_f32_e32 v206, v202
	v_max_f32_e32 v202, v165, v165
	v_max_f32_e32 v202, 0xda24260, v202
	v_rcp_f32_e32 v207, v202
	v_lshlrev_b32_e32 v202, 16, v203
	v_and_b32_e32 v203, 0xffff0000, v203
	v_pk_mul_f32 v[202:203], v[206:207], v[202:203]
	s_nop 0
	v_pk_mul_f32 v[88:89], v[88:89], v[202:203]
	v_lshlrev_b32_e32 v202, 16, v208
	v_and_b32_e32 v203, 0xffff0000, v208
	v_max_f32_e32 v202, v202, v202
	v_max_f32_e32 v203, v203, v203
	v_max_f32_e32 v202, 0xda24260, v202
	v_max_f32_e32 v203, 0xda24260, v203
	v_rcp_f32_e32 v202, v202
	v_rcp_f32_e32 v203, v203
	v_lshlrev_b32_e32 v206, 16, v204
	v_and_b32_e32 v207, 0xffff0000, v204
	v_lshlrev_b32_e32 v208, 16, v209
	v_and_b32_e32 v209, 0xffff0000, v209
	v_pk_mul_f32 v[202:203], v[202:203], v[206:207]
	v_lshlrev_b32_e32 v204, 16, v205
	v_pk_mul_f32 v[82:83], v[82:83], v[202:203]
	v_max_f32_e32 v202, v208, v208
	v_max_f32_e32 v203, v209, v209
	v_max_f32_e32 v202, 0xda24260, v202
	v_max_f32_e32 v203, 0xda24260, v203
	v_rcp_f32_e32 v202, v202
	v_rcp_f32_e32 v203, v203
	v_and_b32_e32 v205, 0xffff0000, v205
	v_pk_mul_f32 v[202:203], v[202:203], v[204:205]
	s_nop 0
	v_pk_mul_f32 v[84:85], v[84:85], v[202:203]
	s_waitcnt vmcnt(6)
	v_lshlrev_b32_e32 v164, 16, v214
	v_and_b32_e32 v165, 0xffff0000, v214
	v_lshlrev_b32_e32 v166, 16, v215
	v_and_b32_e32 v167, 0xffff0000, v215
	v_max_f32_e32 v214, v164, v164
	v_max_f32_e32 v215, v165, v165
	v_max_f32_e32 v214, 0xda24260, v214
	v_max_f32_e32 v215, 0xda24260, v215
	v_rcp_f32_e32 v214, v214
	v_rcp_f32_e32 v215, v215
	v_lshlrev_b32_e32 v164, 16, v210
	v_and_b32_e32 v165, 0xffff0000, v210
	v_max_f32_e32 v210, v166, v166
	v_pk_mul_f32 v[214:215], v[214:215], v[164:165]
	v_max_f32_e32 v210, 0xda24260, v210
	v_pk_mul_f32 v[110:111], v[110:111], v[214:215]
	v_rcp_f32_e32 v214, v210
	v_max_f32_e32 v210, v167, v167
	v_max_f32_e32 v210, 0xda24260, v210
	v_rcp_f32_e32 v215, v210
	v_lshlrev_b32_e32 v210, 16, v211
	v_and_b32_e32 v211, 0xffff0000, v211
	v_pk_mul_f32 v[210:211], v[214:215], v[210:211]
	s_nop 0
	v_pk_mul_f32 v[112:113], v[112:113], v[210:211]
	v_lshlrev_b32_e32 v210, 16, v216
	v_and_b32_e32 v211, 0xffff0000, v216
	v_max_f32_e32 v210, v210, v210
	v_max_f32_e32 v211, v211, v211
	v_max_f32_e32 v210, 0xda24260, v210
	v_max_f32_e32 v211, 0xda24260, v211
	v_rcp_f32_e32 v210, v210
	v_rcp_f32_e32 v211, v211
	v_lshlrev_b32_e32 v214, 16, v212
	v_and_b32_e32 v215, 0xffff0000, v212
	v_lshlrev_b32_e32 v216, 16, v217
	v_and_b32_e32 v217, 0xffff0000, v217
	v_pk_mul_f32 v[210:211], v[210:211], v[214:215]
	v_lshlrev_b32_e32 v212, 16, v213
	v_pk_mul_f32 v[106:107], v[106:107], v[210:211]
	v_max_f32_e32 v210, v216, v216
	v_max_f32_e32 v211, v217, v217
	v_max_f32_e32 v210, 0xda24260, v210
	v_max_f32_e32 v211, 0xda24260, v211
	v_rcp_f32_e32 v210, v210
	v_rcp_f32_e32 v211, v211
	v_and_b32_e32 v213, 0xffff0000, v213
	v_pk_mul_f32 v[210:211], v[210:211], v[212:213]
	s_nop 0
	v_pk_mul_f32 v[108:109], v[108:109], v[210:211]
	s_waitcnt vmcnt(4)
; DEVI f32x4 ld_bf4(const bf16_t* p) { u32x2 u = *(const u32x2*)p; return (f32x4){bf_lo(u.x), bf_hi(u.x), bf_lo(u.y), bf_hi(u.y)}; }
; DEVI void gemm_tile(const GJob& jb, int brow, int bcol, unsigned char* shm_) {
;     ...
;     if (jb.mode == 7 && (t == 16 || t == 32)) {
;       const int seg = (t >> 4) - 1;
;       const bf16_t* gp = (const bf16_t*)jb.aux + (size_t)(brow + wr * 64 + fr) * NGATE + seg * 2048 + bcol + wc * 32 + fq * 8;
; #pragma unroll
;       for (int ai = 0; ai < 2; ++ai)
; #pragma unroll
;         for (int m = 0; m < 4; ++m)
; #pragma unroll
;           for (int bj = 0; bj < 2; ++bj)
; #pragma unroll
;             for (int n = 0; n < 2; ++n) {
;               const bf16_t* g = gp + (size_t)(ai * HALF + m * 16) * NGATE + bj * HALF + n * 4;
;               const f32x4 g0 = ld_bf4(g), g1 = ld_bf4(g + 2048);
; #pragma unroll
;               for (int e = 0; e < 4; ++e) acc[ai][bj][m][n][e] *= g0[e] * __builtin_amdgcn_rcpf(fmaxf(g1[e], 1e-30f));
;             }
	v_lshlrev_b32_e32 v162, 16, v222
	v_and_b32_e32 v163, 0xffff0000, v222
	v_lshlrev_b32_e32 v164, 16, v223
	v_and_b32_e32 v165, 0xffff0000, v223
	v_max_f32_e32 v222, v162, v162
	v_max_f32_e32 v223, v163, v163
	v_max_f32_e32 v222, 0xda24260, v222
	v_max_f32_e32 v223, 0xda24260, v223
	v_rcp_f32_e32 v222, v222
	v_rcp_f32_e32 v223, v223
	v_lshlrev_b32_e32 v162, 16, v218
	v_and_b32_e32 v163, 0xffff0000, v218
	v_max_f32_e32 v218, v164, v164
	v_pk_mul_f32 v[222:223], v[222:223], v[162:163]
	v_max_f32_e32 v218, 0xda24260, v218
	v_pk_mul_f32 v[78:79], v[78:79], v[222:223]
	v_rcp_f32_e32 v222, v218
	v_max_f32_e32 v218, v165, v165
	v_max_f32_e32 v218, 0xda24260, v218
	v_rcp_f32_e32 v223, v218
	v_lshlrev_b32_e32 v218, 16, v219
	v_and_b32_e32 v219, 0xffff0000, v219
	v_pk_mul_f32 v[218:219], v[222:223], v[218:219]
	s_nop 0
	v_pk_mul_f32 v[80:81], v[80:81], v[218:219]
	v_lshlrev_b32_e32 v218, 16, v224
	v_and_b32_e32 v219, 0xffff0000, v224
	v_max_f32_e32 v218, v218, v218
	v_max_f32_e32 v219, v219, v219
	v_max_f32_e32 v218, 0xda24260, v218
	v_max_f32_e32 v219, 0xda24260, v219
	v_rcp_f32_e32 v218, v218
	v_rcp_f32_e32 v219, v219
	v_lshlrev_b32_e32 v222, 16, v220
	v_and_b32_e32 v223, 0xffff0000, v220
	v_lshlrev_b32_e32 v224, 16, v225
	v_and_b32_e32 v225, 0xffff0000, v225
	v_pk_mul_f32 v[218:219], v[218:219], v[222:223]
	v_lshlrev_b32_e32 v220, 16, v221
	v_pk_mul_f32 v[74:75], v[74:75], v[218:219]
	v_max_f32_e32 v218, v224, v224
	v_max_f32_e32 v219, v225, v225
	v_max_f32_e32 v218, 0xda24260, v218
	v_max_f32_e32 v219, 0xda24260, v219
	v_rcp_f32_e32 v218, v218
	v_rcp_f32_e32 v219, v219
	v_and_b32_e32 v221, 0xffff0000, v221
	v_pk_mul_f32 v[218:219], v[218:219], v[220:221]
	s_nop 0
	v_pk_mul_f32 v[76:77], v[76:77], v[218:219]
	s_waitcnt vmcnt(2)
	v_lshlrev_b32_e32 v164, 16, v230
	v_and_b32_e32 v165, 0xffff0000, v230
	v_lshlrev_b32_e32 v166, 16, v231
	v_and_b32_e32 v167, 0xffff0000, v231
	v_max_f32_e32 v230, v164, v164
	v_max_f32_e32 v231, v165, v165
	v_max_f32_e32 v230, 0xda24260, v230
	v_max_f32_e32 v231, 0xda24260, v231
	v_rcp_f32_e32 v230, v230
	v_rcp_f32_e32 v231, v231
	v_lshlrev_b32_e32 v164, 16, v226
	v_and_b32_e32 v165, 0xffff0000, v226
	v_max_f32_e32 v226, v166, v166
	v_pk_mul_f32 v[230:231], v[230:231], v[164:165]
	v_max_f32_e32 v226, 0xda24260, v226
	v_pk_mul_f32 v[102:103], v[102:103], v[230:231]
	v_rcp_f32_e32 v230, v226
	v_max_f32_e32 v226, v167, v167
	v_max_f32_e32 v226, 0xda24260, v226
	v_rcp_f32_e32 v231, v226
	v_lshlrev_b32_e32 v226, 16, v227
	v_and_b32_e32 v227, 0xffff0000, v227
	v_pk_mul_f32 v[226:227], v[230:231], v[226:227]
	s_nop 0
	v_pk_mul_f32 v[104:105], v[104:105], v[226:227]
	v_lshlrev_b32_e32 v226, 16, v232
	v_and_b32_e32 v227, 0xffff0000, v232
	v_max_f32_e32 v226, v226, v226
	v_max_f32_e32 v227, v227, v227
	v_max_f32_e32 v226, 0xda24260, v226
	v_max_f32_e32 v227, 0xda24260, v227
	v_rcp_f32_e32 v226, v226
	v_rcp_f32_e32 v227, v227
	v_lshlrev_b32_e32 v230, 16, v228
	v_and_b32_e32 v231, 0xffff0000, v228
	v_lshlrev_b32_e32 v232, 16, v233
	v_and_b32_e32 v233, 0xffff0000, v233
	v_pk_mul_f32 v[226:227], v[226:227], v[230:231]
	v_lshlrev_b32_e32 v228, 16, v229
	v_pk_mul_f32 v[98:99], v[98:99], v[226:227]
	v_max_f32_e32 v226, v232, v232
	v_max_f32_e32 v227, v233, v233
	v_max_f32_e32 v226, 0xda24260, v226
	v_max_f32_e32 v227, 0xda24260, v227
	v_rcp_f32_e32 v226, v226
	v_rcp_f32_e32 v227, v227
	v_and_b32_e32 v229, 0xffff0000, v229
	v_pk_mul_f32 v[226:227], v[226:227], v[228:229]
	s_nop 0
	v_pk_mul_f32 v[100:101], v[100:101], v[226:227]
	s_waitcnt vmcnt(0)
	v_lshlrev_b32_e32 v162, 16, v238
	v_and_b32_e32 v163, 0xffff0000, v238
	v_lshlrev_b32_e32 v164, 16, v239
	v_and_b32_e32 v165, 0xffff0000, v239
	v_max_f32_e32 v238, v162, v162
	v_max_f32_e32 v239, v163, v163
	v_max_f32_e32 v238, 0xda24260, v238
	v_max_f32_e32 v239, 0xda24260, v239
	v_rcp_f32_e32 v238, v238
	v_rcp_f32_e32 v239, v239
	v_lshlrev_b32_e32 v162, 16, v234
	v_and_b32_e32 v163, 0xffff0000, v234
	v_max_f32_e32 v234, v164, v164
	v_pk_mul_f32 v[238:239], v[238:239], v[162:163]
	v_max_f32_e32 v234, 0xda24260, v234
	v_pk_mul_f32 v[70:71], v[70:71], v[238:239]
	v_rcp_f32_e32 v238, v234
	v_max_f32_e32 v234, v165, v165
	v_max_f32_e32 v234, 0xda24260, v234
	v_rcp_f32_e32 v239, v234
	v_lshlrev_b32_e32 v234, 16, v235
	v_and_b32_e32 v235, 0xffff0000, v235
	v_pk_mul_f32 v[234:235], v[238:239], v[234:235]
	s_nop 0
	v_pk_mul_f32 v[72:73], v[72:73], v[234:235]
	v_lshlrev_b32_e32 v234, 16, v240
	v_and_b32_e32 v235, 0xffff0000, v240
	v_max_f32_e32 v234, v234, v234
	v_max_f32_e32 v235, v235, v235
	v_max_f32_e32 v234, 0xda24260, v234
	v_max_f32_e32 v235, 0xda24260, v235
	v_rcp_f32_e32 v234, v234
	v_rcp_f32_e32 v235, v235
	v_lshlrev_b32_e32 v238, 16, v236
	v_and_b32_e32 v239, 0xffff0000, v236
	v_lshlrev_b32_e32 v240, 16, v241
	v_and_b32_e32 v241, 0xffff0000, v241
	v_pk_mul_f32 v[234:235], v[234:235], v[238:239]
	v_lshlrev_b32_e32 v236, 16, v237
	v_pk_mul_f32 v[66:67], v[66:67], v[234:235]
	v_max_f32_e32 v234, v240, v240
	v_max_f32_e32 v235, v241, v241
	v_max_f32_e32 v234, 0xda24260, v234
	v_max_f32_e32 v235, 0xda24260, v235
	v_rcp_f32_e32 v234, v234
	v_rcp_f32_e32 v235, v235
	v_and_b32_e32 v237, 0xffff0000, v237
	v_pk_mul_f32 v[234:235], v[234:235], v[236:237]
	s_nop 0
	v_pk_mul_f32 v[68:69], v[68:69], v[234:235]
	v_add_co_u32_e32 v130, vcc, s0, v140
	s_mov_b32 s0, 0xfff6eff8
	s_nop 0
	v_addc_co_u32_e32 v131, vcc, -1, v141, vcc
	v_add_co_u32_e32 v162, vcc, s0, v140
	global_load_dwordx4 v[130:133], v[130:131], off
	s_nop 0
	v_addc_co_u32_e32 v163, vcc, -1, v141, vcc
	global_load_dwordx4 v[134:137], v[162:163], off offset:3840
	s_mov_b32 s0, 0xfff6fff8
	v_add_co_u32_e32 v174, vcc, s0, v140
; DEVI f32x4 ld_bf4(const bf16_t* p) { u32x2 u = *(const u32x2*)p; return (f32x4){bf_lo(u.x), bf_hi(u.x), bf_lo(u.y), bf_hi(u.y)}; }
; DEVI void gemm_tile(const GJob& jb, int brow, int bcol, unsigned char* shm_) {
;     ...
;     if (jb.mode == 7 && (t == 16 || t == 32)) {
;       const int seg = (t >> 4) - 1;
;       const bf16_t* gp = (const bf16_t*)jb.aux + (size_t)(brow + wr * 64 + fr) * NGATE + seg * 2048 + bcol + wc * 32 + fq * 8;
; #pragma unroll
;       for (int ai = 0; ai < 2; ++ai)
; #pragma unroll
;         for (int m = 0; m < 4; ++m)
; #pragma unroll
;           for (int bj = 0; bj < 2; ++bj)
; #pragma unroll
;             for (int n = 0; n < 2; ++n) {
;               const bf16_t* g = gp + (size_t)(ai * HALF + m * 16) * NGATE + bj * HALF + n * 4;
;               const f32x4 g0 = ld_bf4(g), g1 = ld_bf4(g + 2048);
; #pragma unroll
;               for (int e = 0; e < 4; ++e) acc[ai][bj][m][n][e] *= g0[e] * __builtin_amdgcn_rcpf(fmaxf(g1[e], 1e-30f));
;             }
	v_addc_co_u32_e32 v175, vcc, -1, v141, vcc
	global_load_dwordx4 v[170:173], v[162:163], off
	s_mov_b32 s0, 0xfff9eef8
	global_load_dwordx4 v[174:177], v[174:175], off
	v_add_co_u32_e32 v194, vcc, s0, v140
	s_mov_b32 s0, 0xfff9eff8
	s_nop 0
	v_addc_co_u32_e32 v195, vcc, -1, v141, vcc
	v_add_co_u32_e32 v162, vcc, s0, v140
	global_load_dwordx4 v[194:197], v[194:195], off
	s_nop 0
	v_addc_co_u32_e32 v163, vcc, -1, v141, vcc
	global_load_dwordx4 v[198:201], v[162:163], off offset:3840
	s_mov_b32 s0, 0xfff9fff8
	v_add_co_u32_e32 v206, vcc, s0, v140
	v_addc_co_u32_e32 v207, vcc, -1, v141, vcc
	global_load_dwordx4 v[202:205], v[162:163], off
	s_mov_b32 s0, 0xfffceef8
	global_load_dwordx4 v[206:209], v[206:207], off
	v_add_co_u32_e32 v210, vcc, s0, v140
	s_mov_b32 s0, 0xfffceff8
	s_nop 0
	v_addc_co_u32_e32 v211, vcc, -1, v141, vcc
	v_add_co_u32_e32 v162, vcc, s0, v140
	global_load_dwordx4 v[210:213], v[210:211], off
	s_nop 0
	v_addc_co_u32_e32 v163, vcc, -1, v141, vcc
	global_load_dwordx4 v[214:217], v[162:163], off offset:3840
	s_mov_b32 s0, 0xfffcfff8
	v_add_co_u32_e32 v222, vcc, s0, v140
	v_addc_co_u32_e32 v223, vcc, -1, v141, vcc
	global_load_dwordx4 v[218:221], v[162:163], off
	s_movk_i32 s0, 0xeef8
	global_load_dwordx4 v[222:225], v[222:223], off
	v_add_co_u32_e32 v226, vcc, s0, v140
	s_movk_i32 s0, 0xeff8
	s_nop 0
	v_addc_co_u32_e32 v227, vcc, -1, v141, vcc
	v_add_co_u32_e32 v162, vcc, s0, v140
	global_load_dwordx4 v[226:229], v[226:227], off
	s_nop 0
	v_addc_co_u32_e32 v163, vcc, -1, v141, vcc
	global_load_dwordx4 v[230:233], v[162:163], off offset:3840
	v_add_co_u32_e32 v238, vcc, -8, v140
	v_addc_co_u32_e32 v239, vcc, -1, v141, vcc
	global_load_dwordx4 v[234:237], v[162:163], off
	s_nop 0
	global_load_dwordx4 v[238:241], v[238:239], off
	s_waitcnt vmcnt(14)
	v_lshlrev_b32_e32 v164, 16, v134
	v_and_b32_e32 v165, 0xffff0000, v134
	v_lshlrev_b32_e32 v166, 16, v135
	v_and_b32_e32 v167, 0xffff0000, v135
	v_max_f32_e32 v134, v164, v164
	v_max_f32_e32 v135, v165, v165
	v_max_f32_e32 v134, 0xda24260, v134
	v_max_f32_e32 v135, 0xda24260, v135
	v_rcp_f32_e32 v134, v134
	v_rcp_f32_e32 v135, v135
	v_lshlrev_b32_e32 v164, 16, v130
	v_and_b32_e32 v165, 0xffff0000, v130
	v_max_f32_e32 v130, v166, v166
	v_pk_mul_f32 v[134:135], v[134:135], v[164:165]
	v_max_f32_e32 v130, 0xda24260, v130
	v_pk_mul_f32 v[62:63], v[62:63], v[134:135]
	v_rcp_f32_e32 v134, v130
	v_max_f32_e32 v130, v167, v167
	v_max_f32_e32 v130, 0xda24260, v130
	v_rcp_f32_e32 v135, v130
	v_lshlrev_b32_e32 v130, 16, v131
	v_and_b32_e32 v131, 0xffff0000, v131
	v_pk_mul_f32 v[130:131], v[134:135], v[130:131]
	s_nop 0
	v_pk_mul_f32 v[64:65], v[64:65], v[130:131]
	v_lshlrev_b32_e32 v130, 16, v136
	v_and_b32_e32 v131, 0xffff0000, v136
	v_max_f32_e32 v130, v130, v130
	v_max_f32_e32 v131, v131, v131
	v_max_f32_e32 v130, 0xda24260, v130
	v_max_f32_e32 v131, 0xda24260, v131
	v_rcp_f32_e32 v130, v130
	v_rcp_f32_e32 v131, v131
	v_lshlrev_b32_e32 v134, 16, v132
	v_and_b32_e32 v135, 0xffff0000, v132
	v_lshlrev_b32_e32 v136, 16, v137
	v_and_b32_e32 v137, 0xffff0000, v137
	v_pk_mul_f32 v[130:131], v[130:131], v[134:135]
	v_lshlrev_b32_e32 v132, 16, v133
	v_pk_mul_f32 v[58:59], v[58:59], v[130:131]
	v_max_f32_e32 v130, v136, v136
	v_max_f32_e32 v131, v137, v137
	v_max_f32_e32 v130, 0xda24260, v130
	v_max_f32_e32 v131, 0xda24260, v131
	v_rcp_f32_e32 v130, v130
	v_rcp_f32_e32 v131, v131
	v_and_b32_e32 v133, 0xffff0000, v133
	v_pk_mul_f32 v[130:131], v[130:131], v[132:133]
	s_nop 0
	v_pk_mul_f32 v[60:61], v[60:61], v[130:131]
	s_waitcnt vmcnt(12)
	v_lshlrev_b32_e32 v162, 16, v174
	v_and_b32_e32 v163, 0xffff0000, v174
	v_lshlrev_b32_e32 v164, 16, v175
	v_and_b32_e32 v165, 0xffff0000, v175
	v_max_f32_e32 v174, v162, v162
	v_max_f32_e32 v175, v163, v163
	v_max_f32_e32 v174, 0xda24260, v174
	v_max_f32_e32 v175, 0xda24260, v175
	v_rcp_f32_e32 v174, v174
	v_rcp_f32_e32 v175, v175
	v_lshlrev_b32_e32 v162, 16, v170
	v_and_b32_e32 v163, 0xffff0000, v170
	v_max_f32_e32 v170, v164, v164
	v_pk_mul_f32 v[174:175], v[174:175], v[162:163]
	v_max_f32_e32 v170, 0xda24260, v170
	v_pk_mul_f32 v[30:31], v[30:31], v[174:175]
	v_rcp_f32_e32 v174, v170
	v_max_f32_e32 v170, v165, v165
	v_max_f32_e32 v170, 0xda24260, v170
	v_rcp_f32_e32 v175, v170
	v_lshlrev_b32_e32 v170, 16, v171
	v_and_b32_e32 v171, 0xffff0000, v171
	v_pk_mul_f32 v[170:171], v[174:175], v[170:171]
	s_nop 0
	v_pk_mul_f32 v[32:33], v[32:33], v[170:171]
	v_lshlrev_b32_e32 v170, 16, v176
	v_and_b32_e32 v171, 0xffff0000, v176
	v_max_f32_e32 v170, v170, v170
	v_max_f32_e32 v171, v171, v171
	v_max_f32_e32 v170, 0xda24260, v170
	v_max_f32_e32 v171, 0xda24260, v171
	v_rcp_f32_e32 v170, v170
	v_rcp_f32_e32 v171, v171
	v_lshlrev_b32_e32 v174, 16, v172
	v_and_b32_e32 v175, 0xffff0000, v172
	v_lshlrev_b32_e32 v176, 16, v177
	v_and_b32_e32 v177, 0xffff0000, v177
	v_pk_mul_f32 v[170:171], v[170:171], v[174:175]
	v_lshlrev_b32_e32 v172, 16, v173
	v_pk_mul_f32 v[26:27], v[26:27], v[170:171]
	v_max_f32_e32 v170, v176, v176
	v_max_f32_e32 v171, v177, v177
	v_max_f32_e32 v170, 0xda24260, v170
	v_max_f32_e32 v171, 0xda24260, v171
	v_rcp_f32_e32 v170, v170
	v_rcp_f32_e32 v171, v171
	v_and_b32_e32 v173, 0xffff0000, v173
	v_pk_mul_f32 v[170:171], v[170:171], v[172:173]
	s_nop 0
	v_pk_mul_f32 v[28:29], v[28:29], v[170:171]
	s_waitcnt vmcnt(10)
; DEVI f32x4 ld_bf4(const bf16_t* p) { u32x2 u = *(const u32x2*)p; return (f32x4){bf_lo(u.x), bf_hi(u.x), bf_lo(u.y), bf_hi(u.y)}; }
; DEVI void gemm_tile(const GJob& jb, int brow, int bcol, unsigned char* shm_) {
;     ...
;     if (jb.mode == 7 && (t == 16 || t == 32)) {
;       const int seg = (t >> 4) - 1;
;       const bf16_t* gp = (const bf16_t*)jb.aux + (size_t)(brow + wr * 64 + fr) * NGATE + seg * 2048 + bcol + wc * 32 + fq * 8;
; #pragma unroll
;       for (int ai = 0; ai < 2; ++ai)
; #pragma unroll
;         for (int m = 0; m < 4; ++m)
; #pragma unroll
;           for (int bj = 0; bj < 2; ++bj)
; #pragma unroll
;             for (int n = 0; n < 2; ++n) {
;               const bf16_t* g = gp + (size_t)(ai * HALF + m * 16) * NGATE + bj * HALF + n * 4;
;               const f32x4 g0 = ld_bf4(g), g1 = ld_bf4(g + 2048);
; #pragma unroll
;               for (int e = 0; e < 4; ++e) acc[ai][bj][m][n][e] *= g0[e] * __builtin_amdgcn_rcpf(fmaxf(g1[e], 1e-30f));
;             }
	v_lshlrev_b32_e32 v164, 16, v198
	v_and_b32_e32 v165, 0xffff0000, v198
	v_lshlrev_b32_e32 v166, 16, v199
	v_and_b32_e32 v167, 0xffff0000, v199
	v_max_f32_e32 v198, v164, v164
	v_max_f32_e32 v199, v165, v165
	v_max_f32_e32 v198, 0xda24260, v198
	v_max_f32_e32 v199, 0xda24260, v199
	v_rcp_f32_e32 v198, v198
	v_rcp_f32_e32 v199, v199
	v_lshlrev_b32_e32 v164, 16, v194
	v_and_b32_e32 v165, 0xffff0000, v194
	v_max_f32_e32 v194, v166, v166
	v_pk_mul_f32 v[198:199], v[198:199], v[164:165]
	v_max_f32_e32 v194, 0xda24260, v194
	v_pk_mul_f32 v[54:55], v[54:55], v[198:199]
	v_rcp_f32_e32 v198, v194
	v_max_f32_e32 v194, v167, v167
	v_max_f32_e32 v194, 0xda24260, v194
	v_rcp_f32_e32 v199, v194
	v_lshlrev_b32_e32 v194, 16, v195
	v_and_b32_e32 v195, 0xffff0000, v195
	v_pk_mul_f32 v[194:195], v[198:199], v[194:195]
	s_nop 0
	v_pk_mul_f32 v[56:57], v[56:57], v[194:195]
	v_lshlrev_b32_e32 v194, 16, v200
	v_and_b32_e32 v195, 0xffff0000, v200
	v_max_f32_e32 v194, v194, v194
	v_max_f32_e32 v195, v195, v195
	v_max_f32_e32 v194, 0xda24260, v194
	v_max_f32_e32 v195, 0xda24260, v195
	v_rcp_f32_e32 v194, v194
	v_rcp_f32_e32 v195, v195
	v_lshlrev_b32_e32 v198, 16, v196
	v_and_b32_e32 v199, 0xffff0000, v196
	v_lshlrev_b32_e32 v200, 16, v201
	v_and_b32_e32 v201, 0xffff0000, v201
	v_pk_mul_f32 v[194:195], v[194:195], v[198:199]
	v_lshlrev_b32_e32 v196, 16, v197
	v_pk_mul_f32 v[50:51], v[50:51], v[194:195]
	v_max_f32_e32 v194, v200, v200
	v_max_f32_e32 v195, v201, v201
	v_max_f32_e32 v194, 0xda24260, v194
	v_max_f32_e32 v195, 0xda24260, v195
	v_rcp_f32_e32 v194, v194
	v_rcp_f32_e32 v195, v195
	v_and_b32_e32 v197, 0xffff0000, v197
	v_pk_mul_f32 v[194:195], v[194:195], v[196:197]
	s_nop 0
	v_pk_mul_f32 v[52:53], v[52:53], v[194:195]
	s_waitcnt vmcnt(8)
	v_lshlrev_b32_e32 v162, 16, v206
	v_and_b32_e32 v163, 0xffff0000, v206
	v_lshlrev_b32_e32 v164, 16, v207
	v_and_b32_e32 v165, 0xffff0000, v207
	v_max_f32_e32 v206, v162, v162
	v_max_f32_e32 v207, v163, v163
	v_max_f32_e32 v206, 0xda24260, v206
	v_max_f32_e32 v207, 0xda24260, v207
	v_rcp_f32_e32 v206, v206
	v_rcp_f32_e32 v207, v207
	v_lshlrev_b32_e32 v162, 16, v202
	v_and_b32_e32 v163, 0xffff0000, v202
	v_max_f32_e32 v202, v164, v164
	v_pk_mul_f32 v[206:207], v[206:207], v[162:163]
	v_max_f32_e32 v202, 0xda24260, v202
	v_pk_mul_f32 v[22:23], v[22:23], v[206:207]
	v_rcp_f32_e32 v206, v202
	v_max_f32_e32 v202, v165, v165
	v_max_f32_e32 v202, 0xda24260, v202
	v_rcp_f32_e32 v207, v202
	v_lshlrev_b32_e32 v202, 16, v203
	v_and_b32_e32 v203, 0xffff0000, v203
	v_pk_mul_f32 v[202:203], v[206:207], v[202:203]
	s_nop 0
	v_pk_mul_f32 v[24:25], v[24:25], v[202:203]
	v_lshlrev_b32_e32 v202, 16, v208
	v_and_b32_e32 v203, 0xffff0000, v208
	v_max_f32_e32 v202, v202, v202
	v_max_f32_e32 v203, v203, v203
	v_max_f32_e32 v202, 0xda24260, v202
	v_max_f32_e32 v203, 0xda24260, v203
	v_rcp_f32_e32 v202, v202
	v_rcp_f32_e32 v203, v203
	v_lshlrev_b32_e32 v206, 16, v204
	v_and_b32_e32 v207, 0xffff0000, v204
	v_lshlrev_b32_e32 v208, 16, v209
	v_and_b32_e32 v209, 0xffff0000, v209
	v_pk_mul_f32 v[202:203], v[202:203], v[206:207]
	v_lshlrev_b32_e32 v204, 16, v205
	v_pk_mul_f32 v[18:19], v[18:19], v[202:203]
	v_max_f32_e32 v202, v208, v208
	v_max_f32_e32 v203, v209, v209
	v_max_f32_e32 v202, 0xda24260, v202
	v_max_f32_e32 v203, 0xda24260, v203
	v_rcp_f32_e32 v202, v202
	v_rcp_f32_e32 v203, v203
	v_and_b32_e32 v205, 0xffff0000, v205
	v_pk_mul_f32 v[202:203], v[202:203], v[204:205]
	s_nop 0
	v_pk_mul_f32 v[20:21], v[20:21], v[202:203]
	s_waitcnt vmcnt(6)
	v_lshlrev_b32_e32 v164, 16, v214
	v_and_b32_e32 v165, 0xffff0000, v214
	v_lshlrev_b32_e32 v166, 16, v215
	v_and_b32_e32 v167, 0xffff0000, v215
	v_max_f32_e32 v214, v164, v164
	v_max_f32_e32 v215, v165, v165
	v_max_f32_e32 v214, 0xda24260, v214
	v_max_f32_e32 v215, 0xda24260, v215
	v_rcp_f32_e32 v214, v214
	v_rcp_f32_e32 v215, v215
	v_lshlrev_b32_e32 v164, 16, v210
	v_and_b32_e32 v165, 0xffff0000, v210
	v_max_f32_e32 v210, v166, v166
	v_pk_mul_f32 v[214:215], v[214:215], v[164:165]
	v_max_f32_e32 v210, 0xda24260, v210
	v_pk_mul_f32 v[46:47], v[46:47], v[214:215]
	v_rcp_f32_e32 v214, v210
	v_max_f32_e32 v210, v167, v167
	v_max_f32_e32 v210, 0xda24260, v210
	v_rcp_f32_e32 v215, v210
	v_lshlrev_b32_e32 v210, 16, v211
	v_and_b32_e32 v211, 0xffff0000, v211
	v_pk_mul_f32 v[210:211], v[214:215], v[210:211]
	s_nop 0
	v_pk_mul_f32 v[48:49], v[48:49], v[210:211]
	v_lshlrev_b32_e32 v210, 16, v216
	v_and_b32_e32 v211, 0xffff0000, v216
	v_max_f32_e32 v210, v210, v210
	v_max_f32_e32 v211, v211, v211
	v_max_f32_e32 v210, 0xda24260, v210
	v_max_f32_e32 v211, 0xda24260, v211
	v_rcp_f32_e32 v210, v210
	v_rcp_f32_e32 v211, v211
	v_lshlrev_b32_e32 v214, 16, v212
	v_and_b32_e32 v215, 0xffff0000, v212
	v_lshlrev_b32_e32 v216, 16, v217
	v_and_b32_e32 v217, 0xffff0000, v217
	v_pk_mul_f32 v[210:211], v[210:211], v[214:215]
	v_lshlrev_b32_e32 v212, 16, v213
	v_pk_mul_f32 v[42:43], v[42:43], v[210:211]
	v_max_f32_e32 v210, v216, v216
	v_max_f32_e32 v211, v217, v217
	v_max_f32_e32 v210, 0xda24260, v210
	v_max_f32_e32 v211, 0xda24260, v211
	v_rcp_f32_e32 v210, v210
	v_rcp_f32_e32 v211, v211
	v_and_b32_e32 v213, 0xffff0000, v213
	v_pk_mul_f32 v[210:211], v[210:211], v[212:213]
	s_nop 0
	v_pk_mul_f32 v[44:45], v[44:45], v[210:211]
	s_waitcnt vmcnt(4)
; DEVI f32x4 ld_bf4(const bf16_t* p) { u32x2 u = *(const u32x2*)p; return (f32x4){bf_lo(u.x), bf_hi(u.x), bf_lo(u.y), bf_hi(u.y)}; }
; DEVI void gemm_tile(const GJob& jb, int brow, int bcol, unsigned char* shm_) {
;     ...
;     if (jb.mode == 7 && (t == 16 || t == 32)) {
;       const int seg = (t >> 4) - 1;
;       const bf16_t* gp = (const bf16_t*)jb.aux + (size_t)(brow + wr * 64 + fr) * NGATE + seg * 2048 + bcol + wc * 32 + fq * 8;
; #pragma unroll
;       for (int ai = 0; ai < 2; ++ai)
; #pragma unroll
;         for (int m = 0; m < 4; ++m)
; #pragma unroll
;           for (int bj = 0; bj < 2; ++bj)
; #pragma unroll
;             for (int n = 0; n < 2; ++n) {
;               const bf16_t* g = gp + (size_t)(ai * HALF + m * 16) * NGATE + bj * HALF + n * 4;
;               const f32x4 g0 = ld_bf4(g), g1 = ld_bf4(g + 2048);
; #pragma unroll
;               for (int e = 0; e < 4; ++e) acc[ai][bj][m][n][e] *= g0[e] * __builtin_amdgcn_rcpf(fmaxf(g1[e], 1e-30f));
;             }
	v_lshlrev_b32_e32 v162, 16, v222
	v_and_b32_e32 v163, 0xffff0000, v222
	v_lshlrev_b32_e32 v164, 16, v223
	v_and_b32_e32 v165, 0xffff0000, v223
	v_max_f32_e32 v222, v162, v162
	v_max_f32_e32 v223, v163, v163
	v_max_f32_e32 v222, 0xda24260, v222
	v_max_f32_e32 v223, 0xda24260, v223
	v_rcp_f32_e32 v222, v222
	v_rcp_f32_e32 v223, v223
	v_lshlrev_b32_e32 v162, 16, v218
	v_and_b32_e32 v163, 0xffff0000, v218
	v_max_f32_e32 v218, v164, v164
	v_pk_mul_f32 v[222:223], v[222:223], v[162:163]
	v_max_f32_e32 v218, 0xda24260, v218
	v_pk_mul_f32 v[14:15], v[14:15], v[222:223]
	v_rcp_f32_e32 v222, v218
	v_max_f32_e32 v218, v165, v165
	v_max_f32_e32 v218, 0xda24260, v218
	v_rcp_f32_e32 v223, v218
	v_lshlrev_b32_e32 v218, 16, v219
	v_and_b32_e32 v219, 0xffff0000, v219
	v_pk_mul_f32 v[218:219], v[222:223], v[218:219]
	s_nop 0
	v_pk_mul_f32 v[16:17], v[16:17], v[218:219]
	v_lshlrev_b32_e32 v218, 16, v224
	v_and_b32_e32 v219, 0xffff0000, v224
	v_max_f32_e32 v218, v218, v218
	v_max_f32_e32 v219, v219, v219
	v_max_f32_e32 v218, 0xda24260, v218
	v_max_f32_e32 v219, 0xda24260, v219
	v_rcp_f32_e32 v218, v218
	v_rcp_f32_e32 v219, v219
	v_lshlrev_b32_e32 v222, 16, v220
	v_and_b32_e32 v223, 0xffff0000, v220
	v_lshlrev_b32_e32 v224, 16, v225
	v_and_b32_e32 v225, 0xffff0000, v225
	v_pk_mul_f32 v[218:219], v[218:219], v[222:223]
	v_lshlrev_b32_e32 v220, 16, v221
	v_pk_mul_f32 v[10:11], v[10:11], v[218:219]
	v_max_f32_e32 v218, v224, v224
	v_max_f32_e32 v219, v225, v225
	v_max_f32_e32 v218, 0xda24260, v218
	v_max_f32_e32 v219, 0xda24260, v219
	v_rcp_f32_e32 v218, v218
	v_rcp_f32_e32 v219, v219
	v_and_b32_e32 v221, 0xffff0000, v221
	v_pk_mul_f32 v[218:219], v[218:219], v[220:221]
	s_nop 0
	v_pk_mul_f32 v[12:13], v[12:13], v[218:219]
	s_waitcnt vmcnt(2)
	v_lshlrev_b32_e32 v164, 16, v230
	v_and_b32_e32 v165, 0xffff0000, v230
	v_lshlrev_b32_e32 v166, 16, v231
	v_and_b32_e32 v167, 0xffff0000, v231
	v_max_f32_e32 v230, v164, v164
	v_max_f32_e32 v231, v165, v165
	v_max_f32_e32 v230, 0xda24260, v230
	v_max_f32_e32 v231, 0xda24260, v231
	v_rcp_f32_e32 v230, v230
	v_rcp_f32_e32 v231, v231
	v_lshlrev_b32_e32 v164, 16, v226
	v_and_b32_e32 v165, 0xffff0000, v226
	v_max_f32_e32 v226, v166, v166
	v_pk_mul_f32 v[230:231], v[230:231], v[164:165]
	v_max_f32_e32 v226, 0xda24260, v226
	v_pk_mul_f32 v[38:39], v[38:39], v[230:231]
	v_rcp_f32_e32 v230, v226
	v_max_f32_e32 v226, v167, v167
	v_max_f32_e32 v226, 0xda24260, v226
	v_rcp_f32_e32 v231, v226
	v_lshlrev_b32_e32 v226, 16, v227
	v_and_b32_e32 v227, 0xffff0000, v227
	v_pk_mul_f32 v[226:227], v[230:231], v[226:227]
	s_nop 0
	v_pk_mul_f32 v[40:41], v[40:41], v[226:227]
	v_lshlrev_b32_e32 v226, 16, v232
	v_and_b32_e32 v227, 0xffff0000, v232
	v_max_f32_e32 v226, v226, v226
	v_max_f32_e32 v227, v227, v227
	v_max_f32_e32 v226, 0xda24260, v226
	v_max_f32_e32 v227, 0xda24260, v227
	v_rcp_f32_e32 v226, v226
	v_rcp_f32_e32 v227, v227
	v_lshlrev_b32_e32 v230, 16, v228
	v_and_b32_e32 v231, 0xffff0000, v228
	v_lshlrev_b32_e32 v232, 16, v233
	v_and_b32_e32 v233, 0xffff0000, v233
	v_pk_mul_f32 v[226:227], v[226:227], v[230:231]
	v_lshlrev_b32_e32 v228, 16, v229
	v_pk_mul_f32 v[34:35], v[34:35], v[226:227]
	v_max_f32_e32 v226, v232, v232
	v_max_f32_e32 v227, v233, v233
	v_max_f32_e32 v226, 0xda24260, v226
	v_max_f32_e32 v227, 0xda24260, v227
	v_rcp_f32_e32 v226, v226
	v_rcp_f32_e32 v227, v227
	v_and_b32_e32 v229, 0xffff0000, v229
	v_pk_mul_f32 v[226:227], v[226:227], v[228:229]
	s_nop 0
	v_pk_mul_f32 v[36:37], v[36:37], v[226:227]
	s_waitcnt vmcnt(0)
	v_lshlrev_b32_e32 v162, 16, v238
	v_and_b32_e32 v163, 0xffff0000, v238
	v_lshlrev_b32_e32 v164, 16, v239
	v_and_b32_e32 v165, 0xffff0000, v239
	v_max_f32_e32 v238, v162, v162
	v_max_f32_e32 v239, v163, v163
	v_max_f32_e32 v238, 0xda24260, v238
	v_max_f32_e32 v239, 0xda24260, v239
	v_rcp_f32_e32 v238, v238
	v_rcp_f32_e32 v239, v239
	v_lshlrev_b32_e32 v162, 16, v234
	v_and_b32_e32 v163, 0xffff0000, v234
	v_max_f32_e32 v234, v164, v164
	v_pk_mul_f32 v[238:239], v[238:239], v[162:163]
	v_max_f32_e32 v234, 0xda24260, v234
	v_pk_mul_f32 v[6:7], v[6:7], v[238:239]
	v_rcp_f32_e32 v238, v234
	v_max_f32_e32 v234, v165, v165
	v_max_f32_e32 v234, 0xda24260, v234
	v_rcp_f32_e32 v239, v234
	v_lshlrev_b32_e32 v234, 16, v235
	v_and_b32_e32 v235, 0xffff0000, v235
	v_pk_mul_f32 v[234:235], v[238:239], v[234:235]
	s_nop 0
	v_pk_mul_f32 v[8:9], v[8:9], v[234:235]
	v_lshlrev_b32_e32 v234, 16, v240
	v_and_b32_e32 v235, 0xffff0000, v240
	v_max_f32_e32 v234, v234, v234
	v_max_f32_e32 v235, v235, v235
	v_max_f32_e32 v234, 0xda24260, v234
	v_max_f32_e32 v235, 0xda24260, v235
	v_rcp_f32_e32 v234, v234
	v_rcp_f32_e32 v235, v235
	v_lshlrev_b32_e32 v238, 16, v236
	v_and_b32_e32 v239, 0xffff0000, v236
	v_lshlrev_b32_e32 v240, 16, v241
	v_and_b32_e32 v241, 0xffff0000, v241
	v_pk_mul_f32 v[234:235], v[234:235], v[238:239]
	v_lshlrev_b32_e32 v236, 16, v237
	v_pk_mul_f32 v[2:3], v[2:3], v[234:235]
	v_max_f32_e32 v234, v240, v240
	v_max_f32_e32 v235, v241, v241
	v_max_f32_e32 v234, 0xda24260, v234
	v_max_f32_e32 v235, 0xda24260, v235
	v_rcp_f32_e32 v234, v234
	v_rcp_f32_e32 v235, v235
	v_and_b32_e32 v237, 0xffff0000, v237
	v_pk_mul_f32 v[234:235], v[234:235], v[236:237]
	s_nop 0
	v_pk_mul_f32 v[4:5], v[4:5], v[234:235]
	s_branch .LBB0_414

; DEVI float bf_lo(unsigned u) { return __uint_as_float(u << 16); }
; DEVI float bf_hi(unsigned u) { return __uint_as_float(u & 0xffff0000u); }
; DEVI float sigmoidf_(float x) { return 1.f / (1.f + __expf(-x)); }
; DEVI u32x4 pack8(f32x4 a, f32x4 b) { u32x4 o; o.x = cvt_pk_bf16(a[0], a[1]); o.y = cvt_pk_bf16(a[2], a[3]); o.z = cvt_pk_bf16(b[0], b[1]); o.w = cvt_pk_bf16(b[2], b[3]); return o; }
; DEVI void gemm_epi(const GJob& jb, int row, int col, f32x4 v0, f32x4 v1) {
;   const int mode = jb.mode;
;   if (mode == 0) { *(u32x4*)((bf16_t*)jb.out + (size_t)row * jb.ldo + col) = pack8(v0, v1); }
;   else if (mode == 1) { float* p = (float*)jb.out + (size_t)row * jb.ldo + col; *(f32x4*)p = v0; *(f32x4*)(p + 4) = v1; }
;   else if (mode == 2) { f32x4 s0, s1; for (int i = 0; i < 4; ++i) { s0[i] = sigmoidf_(v0[i]); s1[i] = sigmoidf_(v1[i]); } *(u32x4*)((bf16_t*)jb.out + (size_t)row * jb.ldo + col) = pack8(s0, s1); }
;   else if (mode == 7) {
;     const u32x4 g = *(const u32x4*)((const bf16_t*)jb.aux + (size_t)row * NGATE + 2 * 2048 + col);
;     const f32x4 g0 = {bf_lo(g.x), bf_hi(g.x), bf_lo(g.y), bf_hi(g.y)}, g1 = {bf_lo(g.z), bf_hi(g.z), bf_lo(g.w), bf_hi(g.w)};
;     *(u32x4*)((bf16_t*)jb.out + (size_t)row * 2048 + col) = pack8(g0 * v0, g1 * v1);
; DEVI void gemm_tile(const GJob& jb, int brow, int bcol, unsigned char* shm_) {
;     ...
;   for (int ai = 0; ai < 2; ++ai)
; #pragma unroll
;     for (int m = 0; m < 4; ++m)
; #pragma unroll
;       for (int bj = 0; bj < 2; ++bj)
;         gemm_epi(jb, brow + ai * HALF + wr * 64 + m * 16 + fr, bcol + bj * HALF + wc * 32 + fq * 8, acc[ai][bj][m][0], acc[ai][bj][m][1]);
.LBB0_424:
	v_or_b32_e32 v0, s43, v159
	v_add_u32_e32 v132, s47, v0
	v_or_b32_e32 v0, s12, v158
	v_ashrrev_i32_e32 v133, 31, v132
	v_or_b32_e32 v130, s68, v0
	s_cmp_eq_u32 s71, 6
	s_cbranch_scc1 .Lepi6
	v_mad_i64_i32 v[136:137], s[0:1], v132, s33, 0
	v_lshlrev_b64 v[134:135], 12, v[132:133]
	s_mov_b64 s[12:13], -1
	s_mov_b64 s[10:11], 0
	s_cmp_lt_i32 s71, 2
	s_mov_b64 s[8:9], 0
	s_cbranch_scc1 .LBB0_433
	s_cmp_gt_i32 s71, 6
	s_cbranch_scc0 .LBB0_429
	s_cmp_eq_u32 s71, 7
	s_mov_b64 s[8:9], -1
	s_cbranch_scc0 .LBB0_428
	v_ashrrev_i32_e32 v131, 31, v130
	v_lshl_add_u64 v[138:139], s[94:95], 0, v[136:137]
	v_lshlrev_b64 v[142:143], 1, v[130:131]
	v_lshl_add_u64 v[138:139], v[138:139], 0, v[142:143]
	v_add_co_u32_e32 v138, vcc, 0x2000, v138
	v_lshl_add_u64 v[144:145], s[90:91], 0, v[134:135]
	s_nop 0
	v_addc_co_u32_e32 v139, vcc, 0, v139, vcc
	flat_load_dwordx4 v[138:141], v[138:139]
	v_lshl_add_u64 v[142:143], v[144:145], 0, v[142:143]
	s_mov_b64 s[8:9], 0
	s_waitcnt vmcnt(0) lgkmcnt(0)
	v_lshlrev_b32_e32 v144, 16, v138
	v_and_b32_e32 v145, 0xffff0000, v138
	v_lshlrev_b32_e32 v138, 16, v139
	v_and_b32_e32 v139, 0xffff0000, v139
	v_lshlrev_b32_e32 v146, 16, v140
	v_and_b32_e32 v147, 0xffff0000, v140
	v_lshlrev_b32_e32 v140, 16, v141
	v_and_b32_e32 v141, 0xffff0000, v141
	v_pk_mul_f32 v[148:149], v[128:129], v[138:139]
	v_pk_mul_f32 v[138:139], v[126:127], v[144:145]
	v_pk_mul_f32 v[144:145], v[124:125], v[140:141]
	v_pk_mul_f32 v[140:141], v[122:123], v[146:147]
	v_cvt_pk_bf16_f32 v138, v138, v139
	v_cvt_pk_bf16_f32 v139, v148, v149
	s_nop 0
	v_cvt_pk_bf16_f32 v140, v140, v141
	v_cvt_pk_bf16_f32 v141, v144, v145
	flat_store_dwordx4 v[142:143], v[138:141]

; DEVI void gemm_epi(const GJob& jb, int row, int col, f32x4 v0, f32x4 v1) {
;     ...
;     const float* xp = (const float*)jb.aux + (size_t)row * jb.ldo + col; const float* gp = (const float*)jb.aux2 + col;
;     float* op = (float*)jb.out + (size_t)row * jb.ldo + col;
;     const f32x4 x0 = *(const f32x4*)xp, x1 = *(const f32x4*)(xp + 4), t0 = *(const f32x4*)gp, t1 = *(const f32x4*)(gp + 4);
;     *(f32x4*)op = x0 + t0 * v0; *(f32x4*)(op + 4) = x1 + t1 * v1;
; DEVI void gemm_tile(const GJob& jb, int brow, int bcol, unsigned char* shm_) {
;     ...
; #pragma unroll
;   for (int ai = 0; ai < 2; ++ai)
; #pragma unroll
;     for (int m = 0; m < 4; ++m)
; #pragma unroll
;       for (int bj = 0; bj < 2; ++bj)
;         gemm_epi(jb, brow + ai * HALF + wr * 64 + m * 16 + fr, bcol + bj * HALF + wc * 32 + fq * 8, acc[ai][bj][m][0], acc[ai][bj][m][1]);
.Lepi6:
	v_mul_lo_u32 v242, v132, s29
	v_lshlrev_b32_e32 v245, 2, v130
	v_add_lshl_u32 v242, v242, v130, 2
	s_lshl_b32 s8, s29, 6
	s_lshl_b32 s9, s29, 9
	global_load_dwordx4 v[142:145], v245, s[88:89] offset:0
	global_load_dwordx4 v[146:149], v245, s[88:89] offset:16
	global_load_dwordx4 v[150:153], v245, s[88:89] offset:512
	global_load_dwordx4 v[154:157], v245, s[88:89] offset:528
	s_mul_i32 s10, s8, 0
	v_add_u32_e32 v246, s10, v242
	global_load_dwordx4 v[226:229], v246, s[94:95] offset:0
	global_load_dwordx4 v[230:233], v246, s[94:95] offset:16
	global_load_dwordx4 v[234:237], v246, s[94:95] offset:512
	global_load_dwordx4 v[238:241], v246, s[94:95] offset:528
	s_mul_i32 s10, s8, 1
	v_add_u32_e32 v247, s10, v242
	global_load_dwordx4 v[194:197], v247, s[94:95] offset:0
	global_load_dwordx4 v[198:201], v247, s[94:95] offset:16
	global_load_dwordx4 v[214:217], v247, s[94:95] offset:512
	global_load_dwordx4 v[170:173], v247, s[94:95] offset:528
	s_waitcnt vmcnt(4)
	v_pk_fma_f32 v[226:227], v[126:127], v[142:143], v[226:227]
	v_pk_fma_f32 v[228:229], v[128:129], v[144:145], v[228:229]
	v_pk_fma_f32 v[230:231], v[122:123], v[146:147], v[230:231]
	v_pk_fma_f32 v[232:233], v[124:125], v[148:149], v[232:233]
	v_pk_fma_f32 v[234:235], v[118:119], v[150:151], v[234:235]
	v_pk_fma_f32 v[236:237], v[120:121], v[152:153], v[236:237]
	v_pk_fma_f32 v[238:239], v[114:115], v[154:155], v[238:239]
	v_pk_fma_f32 v[240:241], v[116:117], v[156:157], v[240:241]
	global_store_dwordx4 v246, v[226:229], s[90:91] offset:0
	global_store_dwordx4 v246, v[230:233], s[90:91] offset:16
	global_store_dwordx4 v246, v[234:237], s[90:91] offset:512
	global_store_dwordx4 v246, v[238:241], s[90:91] offset:528
	s_mul_i32 s10, s8, 2
	v_add_u32_e32 v248, s10, v242
	global_load_dwordx4 v[126:129], v248, s[94:95] offset:0
	global_load_dwordx4 v[122:125], v248, s[94:95] offset:16
	global_load_dwordx4 v[118:121], v248, s[94:95] offset:512
	global_load_dwordx4 v[114:117], v248, s[94:95] offset:528
	s_waitcnt vmcnt(8)
	v_pk_fma_f32 v[194:195], v[110:111], v[142:143], v[194:195]
	v_pk_fma_f32 v[196:197], v[112:113], v[144:145], v[196:197]
	v_pk_fma_f32 v[198:199], v[106:107], v[146:147], v[198:199]
	v_pk_fma_f32 v[200:201], v[108:109], v[148:149], v[200:201]
	v_pk_fma_f32 v[214:215], v[102:103], v[150:151], v[214:215]
	v_pk_fma_f32 v[216:217], v[104:105], v[152:153], v[216:217]
	v_pk_fma_f32 v[170:171], v[98:99], v[154:155], v[170:171]
	v_pk_fma_f32 v[172:173], v[100:101], v[156:157], v[172:173]
	global_store_dwordx4 v247, v[194:197], s[90:91] offset:0
	global_store_dwordx4 v247, v[198:201], s[90:91] offset:16
	global_store_dwordx4 v247, v[214:217], s[90:91] offset:512
	global_store_dwordx4 v247, v[170:173], s[90:91] offset:528
	s_mul_i32 s10, s8, 3
	v_add_u32_e32 v246, s10, v242
	global_load_dwordx4 v[110:113], v246, s[94:95] offset:0
	global_load_dwordx4 v[106:109], v246, s[94:95] offset:16
	global_load_dwordx4 v[102:105], v246, s[94:95] offset:512
	global_load_dwordx4 v[98:101], v246, s[94:95] offset:528
	s_waitcnt vmcnt(8)
	v_pk_fma_f32 v[126:127], v[94:95], v[142:143], v[126:127]
	v_pk_fma_f32 v[128:129], v[96:97], v[144:145], v[128:129]
	v_pk_fma_f32 v[122:123], v[90:91], v[146:147], v[122:123]
	v_pk_fma_f32 v[124:125], v[92:93], v[148:149], v[124:125]
	v_pk_fma_f32 v[118:119], v[86:87], v[150:151], v[118:119]
	v_pk_fma_f32 v[120:121], v[88:89], v[152:153], v[120:121]
	v_pk_fma_f32 v[114:115], v[82:83], v[154:155], v[114:115]
	v_pk_fma_f32 v[116:117], v[84:85], v[156:157], v[116:117]
	global_store_dwordx4 v248, v[126:129], s[90:91] offset:0
	global_store_dwordx4 v248, v[122:125], s[90:91] offset:16
	global_store_dwordx4 v248, v[118:121], s[90:91] offset:512
	global_store_dwordx4 v248, v[114:117], s[90:91] offset:528
	s_mul_i32 s10, s8, 0
	s_add_i32 s10, s10, s9
	v_add_u32_e32 v247, s10, v242
	global_load_dwordx4 v[94:97], v247, s[94:95] offset:0
	global_load_dwordx4 v[90:93], v247, s[94:95] offset:16
	global_load_dwordx4 v[86:89], v247, s[94:95] offset:512
	global_load_dwordx4 v[82:85], v247, s[94:95] offset:528
	s_waitcnt vmcnt(8)
; DEVI void gemm_epi(const GJob& jb, int row, int col, f32x4 v0, f32x4 v1) {
;     ...
;     const float* xp = (const float*)jb.aux + (size_t)row * jb.ldo + col; const float* gp = (const float*)jb.aux2 + col;
;     float* op = (float*)jb.out + (size_t)row * jb.ldo + col;
;     const f32x4 x0 = *(const f32x4*)xp, x1 = *(const f32x4*)(xp + 4), t0 = *(const f32x4*)gp, t1 = *(const f32x4*)(gp + 4);
;     *(f32x4*)op = x0 + t0 * v0; *(f32x4*)(op + 4) = x1 + t1 * v1;
; DEVI void gemm_tile(const GJob& jb, int brow, int bcol, unsigned char* shm_) {
;     ...
;   for (int ai = 0; ai < 2; ++ai)
; #pragma unroll
;     for (int m = 0; m < 4; ++m)
; #pragma unroll
;       for (int bj = 0; bj < 2; ++bj)
;         gemm_epi(jb, brow + ai * HALF + wr * 64 + m * 16 + fr, bcol + bj * HALF + wc * 32 + fq * 8, acc[ai][bj][m][0], acc[ai][bj][m][1]);
	v_pk_fma_f32 v[110:111], v[78:79], v[142:143], v[110:111]
	v_pk_fma_f32 v[112:113], v[80:81], v[144:145], v[112:113]
	v_pk_fma_f32 v[106:107], v[74:75], v[146:147], v[106:107]
	v_pk_fma_f32 v[108:109], v[76:77], v[148:149], v[108:109]
	v_pk_fma_f32 v[102:103], v[70:71], v[150:151], v[102:103]
	v_pk_fma_f32 v[104:105], v[72:73], v[152:153], v[104:105]
	v_pk_fma_f32 v[98:99], v[66:67], v[154:155], v[98:99]
	v_pk_fma_f32 v[100:101], v[68:69], v[156:157], v[100:101]
	global_store_dwordx4 v246, v[110:113], s[90:91] offset:0
	global_store_dwordx4 v246, v[106:109], s[90:91] offset:16
	global_store_dwordx4 v246, v[102:105], s[90:91] offset:512
	global_store_dwordx4 v246, v[98:101], s[90:91] offset:528
	s_mul_i32 s10, s8, 1
	s_add_i32 s10, s10, s9
	v_add_u32_e32 v248, s10, v242
	global_load_dwordx4 v[78:81], v248, s[94:95] offset:0
	global_load_dwordx4 v[74:77], v248, s[94:95] offset:16
	global_load_dwordx4 v[70:73], v248, s[94:95] offset:512
	global_load_dwordx4 v[66:69], v248, s[94:95] offset:528
	s_waitcnt vmcnt(8)
	v_pk_fma_f32 v[94:95], v[62:63], v[142:143], v[94:95]
	v_pk_fma_f32 v[96:97], v[64:65], v[144:145], v[96:97]
	v_pk_fma_f32 v[90:91], v[58:59], v[146:147], v[90:91]
	v_pk_fma_f32 v[92:93], v[60:61], v[148:149], v[92:93]
	v_pk_fma_f32 v[86:87], v[54:55], v[150:151], v[86:87]
	v_pk_fma_f32 v[88:89], v[56:57], v[152:153], v[88:89]
	v_pk_fma_f32 v[82:83], v[50:51], v[154:155], v[82:83]
	v_pk_fma_f32 v[84:85], v[52:53], v[156:157], v[84:85]
	global_store_dwordx4 v247, v[94:97], s[90:91] offset:0
	global_store_dwordx4 v247, v[90:93], s[90:91] offset:16
	global_store_dwordx4 v247, v[86:89], s[90:91] offset:512
	global_store_dwordx4 v247, v[82:85], s[90:91] offset:528
	s_mul_i32 s10, s8, 2
	s_add_i32 s10, s10, s9
	v_add_u32_e32 v246, s10, v242
	global_load_dwordx4 v[62:65], v246, s[94:95] offset:0
	global_load_dwordx4 v[58:61], v246, s[94:95] offset:16
	global_load_dwordx4 v[54:57], v246, s[94:95] offset:512
	global_load_dwordx4 v[50:53], v246, s[94:95] offset:528
	s_waitcnt vmcnt(8)
	v_pk_fma_f32 v[78:79], v[46:47], v[142:143], v[78:79]
	v_pk_fma_f32 v[80:81], v[48:49], v[144:145], v[80:81]
	v_pk_fma_f32 v[74:75], v[42:43], v[146:147], v[74:75]
	v_pk_fma_f32 v[76:77], v[44:45], v[148:149], v[76:77]
	v_pk_fma_f32 v[70:71], v[38:39], v[150:151], v[70:71]
	v_pk_fma_f32 v[72:73], v[40:41], v[152:153], v[72:73]
	v_pk_fma_f32 v[66:67], v[34:35], v[154:155], v[66:67]
	v_pk_fma_f32 v[68:69], v[36:37], v[156:157], v[68:69]
	global_store_dwordx4 v248, v[78:81], s[90:91] offset:0
	global_store_dwordx4 v248, v[74:77], s[90:91] offset:16
	global_store_dwordx4 v248, v[70:73], s[90:91] offset:512
	global_store_dwordx4 v248, v[66:69], s[90:91] offset:528
	s_mul_i32 s10, s8, 3
	s_add_i32 s10, s10, s9
	v_add_u32_e32 v247, s10, v242
	global_load_dwordx4 v[46:49], v247, s[94:95] offset:0
	global_load_dwordx4 v[42:45], v247, s[94:95] offset:16
	global_load_dwordx4 v[38:41], v247, s[94:95] offset:512
	global_load_dwordx4 v[34:37], v247, s[94:95] offset:528
	s_waitcnt vmcnt(8)
	v_pk_fma_f32 v[62:63], v[30:31], v[142:143], v[62:63]
	v_pk_fma_f32 v[64:65], v[32:33], v[144:145], v[64:65]
	v_pk_fma_f32 v[58:59], v[26:27], v[146:147], v[58:59]
	v_pk_fma_f32 v[60:61], v[28:29], v[148:149], v[60:61]
	v_pk_fma_f32 v[54:55], v[22:23], v[150:151], v[54:55]
	v_pk_fma_f32 v[56:57], v[24:25], v[152:153], v[56:57]
	v_pk_fma_f32 v[50:51], v[18:19], v[154:155], v[50:51]
	v_pk_fma_f32 v[52:53], v[20:21], v[156:157], v[52:53]
	global_store_dwordx4 v246, v[62:65], s[90:91] offset:0
	global_store_dwordx4 v246, v[58:61], s[90:91] offset:16
	global_store_dwordx4 v246, v[54:57], s[90:91] offset:512
	global_store_dwordx4 v246, v[50:53], s[90:91] offset:528
	s_waitcnt vmcnt(4)
	v_pk_fma_f32 v[46:47], v[14:15], v[142:143], v[46:47]
	v_pk_fma_f32 v[48:49], v[16:17], v[144:145], v[48:49]
	v_pk_fma_f32 v[42:43], v[10:11], v[146:147], v[42:43]
	v_pk_fma_f32 v[44:45], v[12:13], v[148:149], v[44:45]
	v_pk_fma_f32 v[38:39], v[6:7], v[150:151], v[38:39]
	v_pk_fma_f32 v[40:41], v[8:9], v[152:153], v[40:41]
	v_pk_fma_f32 v[34:35], v[2:3], v[154:155], v[34:35]
	v_pk_fma_f32 v[36:37], v[4:5], v[156:157], v[36:37]
	global_store_dwordx4 v247, v[46:49], s[90:91] offset:0
	global_store_dwordx4 v247, v[42:45], s[90:91] offset:16
	global_store_dwordx4 v247, v[38:41], s[90:91] offset:512
	global_store_dwordx4 v247, v[34:37], s[90:91] offset:528
	s_branch .LBB0_409
